# grid barrier: L1/L2 invalidate issued before arrival (no loads happen until release) instead of 256 contended invalidates after release
# speedup vs baseline: 1.0034x; 1.0034x over previous
; DEVI int opaque_tid(int wv) { int t; asm volatile("v_mbcnt_lo_u32_b32 %0, -1, 0\n\tv_mbcnt_hi_u32_b32 %0, -1, %0" : "=v"(t)); return wv * 64 + t; }
; DEVI void gbar(unsigned* ctr, unsigned& gen, int wv) {
;   asm volatile("s_waitcnt vmcnt(0) lgkmcnt(0)" ::: "memory");
;   __syncthreads();
;   ++gen;
;   const int tb = opaque_tid(wv);
;   if (tb < 64) {
;     __builtin_amdgcn_fence(__ATOMIC_RELEASE, "agent");
;     asm volatile("s_waitcnt vmcnt(0)" ::: "memory");
;     if (tb == 0) {
;       __hip_atomic_fetch_add(ctr, 1u, __ATOMIC_RELAXED, __HIP_MEMORY_SCOPE_AGENT);
;       const unsigned target = gen * 256u;
;       while (__hip_atomic_load(ctr, __ATOMIC_RELAXED, __HIP_MEMORY_SCOPE_AGENT) < target) { }
.LBB0_243:
	s_or_b64 exec, exec, s[0:1]
	v_readlane_b32 s0, v252, 40
	v_readlane_b32 s2, v252, 42
	s_waitcnt vmcnt(0) lgkmcnt(0)
	s_barrier
	v_mbcnt_lo_u32_b32 v0, -1, 0
	v_mbcnt_hi_u32_b32 v0, -1, v0
	v_readlane_b32 s0, v252, 46
	v_readlane_b32 s3, v252, 43
	s_add_u32 s52, s2, 0x1f414000
	v_add_u32_e32 v0, s0, v0
	v_readlane_b32 s1, v252, 41
	s_addc_u32 s53, s3, 0
	v_cmp_gt_i32_e32 vcc, 64, v0
	s_and_saveexec_b64 s[0:1], vcc
	s_cbranch_execz .LBB0_250
	s_waitcnt vmcnt(0)
	buffer_inv sc1
	v_cmp_eq_u32_e32 vcc, 0, v0
	s_and_saveexec_b64 s[2:3], vcc
	s_cbranch_execz .LBB0_249
	s_getreg_b32 s6, hwreg(HW_REG_XCC_ID, 0, 4)
	s_lshl_b32 s6, s6, 2
	s_add_u32 s6, s52, s6
	s_addc_u32 s7, s53, 0
	v_mov_b32_e32 v0, 0
	v_mov_b32_e32 v1, 1
	global_atomic_add v1, v0, v1, s[6:7] offset:128 sc0
	s_waitcnt vmcnt(0)
	v_readfirstlane_b32 s4, v1
	s_cmp_lg_u32 s4, 31
	s_cbranch_scc1 .Lgb0_poll
	buffer_wbl2 sc1
	s_waitcnt vmcnt(0)
	v_mov_b32_e32 v1, 1
	global_atomic_add v0, v1, s[52:53]

; DEVI int opaque_tid(int wv) { int t; asm volatile("v_mbcnt_lo_u32_b32 %0, -1, 0\n\tv_mbcnt_hi_u32_b32 %0, -1, %0" : "=v"(t)); return wv * 64 + t; }
;     __host__ __device__ bool next(int i, Unit& u) const {
;         const long L = (long)i * G + c; if (L >= nwg) return false;
;         int wgid = (int)L; { const int q = nwg / NXCD, r = nwg % NXCD, xcd = wgid % NXCD, off = wgid / NXCD; wgid = (xcd < r ? xcd * (q + 1) : r * (q + 1) + (xcd - r) * q) + off; }
;         const int nig = WGM * nN, gid = wgid / nig, fm = gid * WGM, gsz = (nM - fm) < WGM ? (nM - fm) : WGM;
;         u.pm = fm + ((wgid % nig) % gsz); u.pn = (wgid % nig) / gsz; return true;
; __global__ void __launch_bounds__(512) mega(Params p) {
;     ...
;   float* SX = (float*)(ws + WS_SH); float* SPb = SX + 16 * 1024; float* SM = SPb + 16 * SPW; float* SU = SM + 16 * 1024; float* SNAP = SU + 16 * 4096;
;   float* ONES = SNAP + 4 * 16 * 1024;
;   {
;     const int tid = opaque_tid(wv);
;     if (bid < 16) { for (int k = tid; k < DM; k += 512) SX[bid * 1024 + k] = p.in[0][(size_t)bid * S * DM + k]; }
;     if (bid == 16) { for (int k = tid; k < 4096; k += 512) ONES[k] = 1.f; }
;   }
;   int sph = 0;
;   auto shadow_step = [&]() {
;     int bido = bid; asm volatile("" : "+s"(bido));
;     if (sph <= 20 && sph % 5 == 0 && sph > 0 && bido < 16) {
;       const int tid = opaque_tid(wv);
;       for (int k = tid; k < DM; k += 512) SNAP[(size_t)((sph / 5 - 1) * 16 + bido) * 1024 + k] = SX[bido * 1024 + k];
;     }
;     if (sph < 20) {
;       const int l = sph / 5, st = sph % 5;
;       if (st == 0) sk_gemm(SX, 1024, 1024, p.in[3] + (size_t)l * 1024 * 2866, 2866, p.in[2] + l * 1024, true, SPb, SPW, 0, lds, wv, bid, nblk);
;       else if (st == 1) { if (bido >= 240) sk_mixer(p, l, SPb, SM, bido - 240, lds, wv); }
;       else if (st == 2) sk_gemm(SM, 1024, 1024, p.in[15] + (size_t)l * 1024 * 1024, 1024, ONES, false, SX, 1024, 1, lds, wv, bid, nblk);
;       else if (st == 3) sk_gemm(SX, 1024, 1024, p.in[17] + (size_t)l * 1024 * 4096, 4096, p.in[16] + l * 1024, true, SU, 4096, 2, lds, wv, bid, nblk);
;       else sk_gemm(SU, 4096, 4096, p.in[18] + (size_t)l * 4096 * 1024, 1024, ONES, false, SX, 1024, 1, lds, wv, bid, nblk);
;     }
;     ++sph;
;   };
;   unsigned gen = 0; unsigned* barw = cx.ctr + 4096;
;   gbar(barw, gen, wv);
.LBB0_249:
	s_or_b64 exec, exec, s[2:3]
	s_waitcnt vmcnt(0)
.LBB0_250:
	s_or_b64 exec, exec, s[0:1]
	v_readlane_b32 s8, v252, 40
	v_readlane_b32 s10, v252, 42
	v_readlane_b32 s11, v252, 43
	s_add_u32 s0, s10, 0x1f500000
	s_addc_u32 s1, s11, 0
	v_writelane_b32 v253, s0, 12
	v_readlane_b32 s12, v252, 46
	v_readlane_b32 s9, v252, 41
	v_writelane_b32 v253, s1, 13
	s_add_u32 s0, s10, 0x1f510000
	s_addc_u32 s1, s11, 0
	v_writelane_b32 v253, s0, 14
	s_mov_b32 s93, 0
	v_mov_b32_e32 v33, 0
	v_writelane_b32 v253, s1, 15
	s_add_u32 s0, s10, 0x1f53d000
	s_addc_u32 s1, s11, 0
	v_writelane_b32 v253, s0, 16
	v_mov_b32_e32 v224, 0x358637bd
	v_mov_b32_e32 v225, 0xfff
	v_writelane_b32 v253, s1, 17
	s_add_u32 s0, s10, 0x1f54d000
	s_addc_u32 s1, s11, 0
	v_writelane_b32 v253, s0, 18
	v_mov_b32_e32 v226, 0x3ff
	v_mov_b32_e32 v227, 0x7f800000
	v_writelane_b32 v253, s1, 19
	s_add_u32 s0, s10, 0x1f58d000
	v_writelane_b32 v253, s0, 20
	s_addc_u32 s0, s11, 0
	v_writelane_b32 v253, s0, 21
	s_add_u32 s0, s10, 0x1f600000
	s_addc_u32 s1, s11, 0
	v_writelane_b32 v253, s0, 22
	v_mov_b32_e32 v251, 0xb31
	v_mov_b32_e32 v236, 1
	v_writelane_b32 v253, s1, 23
	s_add_u32 s0, s10, 0x1f800000
	s_addc_u32 s1, s11, 0
	s_add_u32 s14, s10, 0x9000000
	v_writelane_b32 v253, s0, 24
	s_addc_u32 s15, s11, 0
	v_mov_b32_e32 v230, 0x3e000000
	v_writelane_b32 v253, s1, 25
	s_add_u32 s0, s10, 0xd000000
	s_addc_u32 s1, s11, 0
	v_writelane_b32 v253, s0, 26
	v_mov_b32_e32 v231, 0xff8
	v_mov_b32_e32 v232, 0x7ffffff8
	v_writelane_b32 v253, s1, 27
	s_add_u32 s0, s10, 0xf000000
	s_addc_u32 s1, s11, 0
	v_writelane_b32 v253, s0, 6
	v_mov_b32_e32 v233, 0x3e38aa3b
	v_mov_b32_e32 v234, 0x7cf
	v_writelane_b32 v253, s1, 7
	s_add_u32 s0, s10, 0xf800000
	s_addc_u32 s1, s11, 0
	s_add_u32 s16, s10, 0x10000000
	v_writelane_b32 v253, s0, 2
	s_addc_u32 s17, s11, 0
	v_mov_b32_e32 v235, 0x7e0
	v_writelane_b32 v253, s1, 3
	s_add_u32 s0, s10, 0x14000000
	s_addc_u32 s1, s11, 0
	v_writelane_b32 v253, s0, 28
	v_bfrev_b32_e32 v237, 0.5
	v_mov_b32_e32 v130, 0xefa18f08
	v_writelane_b32 v253, s1, 29
	s_add_u32 s0, s10, 0x15400000
	s_addc_u32 s1, s11, 0
	v_writelane_b32 v253, s0, 30
	v_mov_b32_e32 v238, 0xf149f2ca
	v_mov_b32_e32 v239, 0x4e6e6b28
	v_writelane_b32 v253, s1, 31
	s_add_u32 s0, s10, 0x16800000
	s_addc_u32 s1, s11, 0
	v_writelane_b32 v253, s0, 32
	v_mov_b64_e32 v[222:223], 0x200
	v_mov_b64_e32 v[228:229], 0x1ff
	v_writelane_b32 v253, s1, 33
	s_add_u32 s0, s10, 0x17c00000
	v_writelane_b32 v253, s0, 34
	s_addc_u32 s0, s11, 0
	v_writelane_b32 v253, s0, 35
	s_add_u32 s0, s10, 0x17e00000
	s_addc_u32 s1, s11, 0
	v_writelane_b32 v253, s0, 36
	s_movk_i32 s74, 0xffc0
	s_movk_i32 s58, 0x80
	v_writelane_b32 v253, s1, 37
	s_add_u32 s0, s10, 0x17e80000
	s_addc_u32 s1, s11, 0
	v_writelane_b32 v253, s0, 38
	s_cmpk_lt_i32 s76, 0x100
	s_movk_i32 s75, 0x2ff
	v_writelane_b32 v253, s1, 39
	s_cselect_b64 s[0:1], -1, 0
	v_writelane_b32 v253, s0, 40
	s_cmp_lt_i32 s76, 64
	s_mov_b32 s77, 0x800000
	v_writelane_b32 v253, s1, 41
	s_cselect_b64 s[0:1], -1, 0
	v_writelane_b32 v253, s0, 42
	s_cmpk_lt_i32 s76, 0xb4
	s_mov_b32 s78, 0xfffe4000
	v_writelane_b32 v253, s1, 43
	s_cselect_b64 s[0:1], -1, 0
	v_writelane_b32 v253, s0, 44
	s_cmpk_lt_i32 s76, 0x600
	s_mov_b32 s79, 0xfffe8000
	v_writelane_b32 v253, s1, 45
	s_cselect_b64 s[0:1], -1, 0
	v_writelane_b32 v253, s0, 46
	s_ashr_i32 s65, s76, 31
	s_sub_i32 s2, 0, s12
	v_writelane_b32 v253, s1, 47
	s_lshr_b32 s0, s65, 29
	s_add_i32 s0, s76, s0
	s_ashr_i32 s1, s0, 3
	s_and_b32 s0, s0, -8
	s_sub_i32 s0, s76, s0
	v_writelane_b32 v253, s2, 48
	s_add_u32 s2, s10, 0x1f410100
	v_writelane_b32 v253, s2, 49
	s_addc_u32 s2, s11, 0
	s_cmpk_lt_i32 s76, 0x200
	v_writelane_b32 v253, s2, 50
	s_cselect_b64 s[2:3], -1, 0
	v_writelane_b32 v253, s2, 51
	s_mov_b32 s80, 0xfffec000
	s_mov_b32 s81, 0xffff0000
	v_writelane_b32 v253, s3, 52
	s_lshl_b32 s2, s0, 6
	s_cmpk_lt_i32 s76, 0x800
	s_cselect_b64 s[4:5], -1, 0
	v_writelane_b32 v253, s4, 53
	s_lshl_b32 s3, s0, 8
	s_cmp_lt_i32 s0, 0
	v_writelane_b32 v253, s5, 54
	s_mul_i32 s4, s0, 0x41
	s_cselect_b32 s2, s4, s2
	s_movk_i32 s4, 0xc1
	s_cselect_b32 s4, s4, 0xc0
	s_mul_i32 s4, s0, s4
	s_mulk_i32 s0, 0x101
	s_cselect_b32 s0, s0, s3
	s_add_i32 s4, s4, s1
	s_mul_hi_i32 s3, s4, 0x2aaaaaab
	s_lshr_b32 s5, s3, 31
	s_ashr_i32 s3, s3, 4
	s_add_i32 s3, s3, s5
	s_mul_i32 s5, s3, 0x60
	s_sub_i32 s4, s4, s5
	s_bfe_i32 s5, s4, 0x80000
	s_bfe_u32 s5, s5, 0x3000c
	s_add_i32 s5, s4, s5
	s_and_b32 s6, s5, 0xf8
	s_add_i32 s2, s2, s1
	s_sub_i32 s4, s4, s6
	s_ashr_i32 s6, s2, 31
	s_lshr_b32 s6, s6, 27
	s_add_i32 s6, s2, s6
	s_and_b32 s7, s6, 0xffe0
	s_sub_i32 s2, s2, s7
	s_bfe_i32 s7, s2, 0x80000
	s_add_i32 s0, s0, s1
	s_bfe_u32 s7, s7, 0x3000c
	s_ashr_i32 s1, s0, 31
	s_add_i32 s7, s2, s7
	s_lshr_b32 s1, s1, 25
	s_and_b32 s8, s7, 0xf8
	s_add_i32 s1, s0, s1
	s_sub_i32 s2, s2, s8
	s_and_b32 s8, s1, 0xff80
	s_sub_i32 s0, s0, s8
	s_bfe_i32 s8, s0, 0x80000
	s_bfe_u32 s8, s8, 0x3000c
	s_lshl_b32 s3, s3, 3
	s_sext_i32_i8 s4, s4
	s_add_i32 s8, s0, s8
	s_add_i32 s18, s3, s4
	s_ashr_i32 s3, s6, 5
	s_and_b32 s9, s8, 0xf8
	s_lshl_b32 s3, s3, 3
	s_sext_i32_i8 s2, s2
	s_sub_i32 s0, s0, s9
	s_add_i32 s6, s3, s2
	s_ashr_i32 s1, s1, 7
	s_bfe_i32 s2, s8, 0x80000
	s_lshl_b32 s1, s1, 3
	s_sext_i32_i16 s2, s2
	s_sext_i32_i8 s0, s0
	s_add_i32 s8, s1, s0
	s_ashr_i32 s0, s2, 3
	v_writelane_b32 v253, s0, 55
	s_lshr_b32 s0, s2, 3
	s_bfe_i64 s[0:1], s[0:1], 0x100000
	s_bfe_i32 s5, s5, 0x80000
	s_lshl_b64 s[0:1], s[0:1], 19
	s_sext_i32_i16 s5, s5
	s_bfe_i32 s4, s7, 0x80000
	v_writelane_b32 v253, s0, 56
	s_sext_i32_i16 s4, s4
	s_lshr_b32 s2, s4, 3
	v_writelane_b32 v253, s1, 57
	s_ashr_i32 s0, s5, 3
	v_writelane_b32 v253, s0, 58
; DEVI int opaque_tid(int wv) { int t; asm volatile("v_mbcnt_lo_u32_b32 %0, -1, 0\n\tv_mbcnt_hi_u32_b32 %0, -1, %0" : "=v"(t)); return wv * 64 + t; }
; #define PG8_LAS __attribute__((address_space(3)))
; template <class Epi, class Sched, bool ALIGN_EPI = false, bool SP2 = false>
; __device__ __forceinline__ void gemm_phase(PG8_LAS unsigned char* lds, const Gemm g, const Sched& S, const Epi& E, int tid_in) {
;     ...
;     const char* cA = (const char*)g.A + (size_t)cur.pm * tstep; const char* cB = (const char*)g.Bt + (size_t)cur.pn * tstep;
; __global__ void __launch_bounds__(512) mega(Params p) {
;     ...
;   for (int l = 0; l < 4; ++l) {
;     shadow_step();
;     {
;       float* ssB = (float*)(ws + WS_SS) + (size_t)T * 16;
;       const int tid = opaque_tid(wv);
;       EpiAdaptInProjPM ep{cx.proj, cx.vslcT, cx.vwinT, cx.retvT, cx.rope, ssB};
;       pg8::Gemm g{cx.xb, cx.win + (size_t)l * NIN * 1024, T, NIN, 1024};
;       pg8::StaticOrder so; so.init(T, NIN, nblk, bid);
;       __syncthreads();
;       pg8::gemm_phase<EpiAdaptInProjPM, pg8::StaticOrder, true, true>((PG8_LAS unsigned char*)lds, g, so, ep, tid);
	s_ashr_i32 s1, s4, 3
	v_writelane_b32 v253, s1, 59
	s_mov_b32 s4, s8
	s_ashr_i32 s9, s8, 31
	s_lshr_b32 s0, s5, 3
	v_writelane_b32 v253, s4, 60
	s_mov_b32 s82, 0xffff4000
	s_movk_i32 s83, 0x8000
	v_writelane_b32 v253, s5, 61
	s_lshl_b64 s[4:5], s[8:9], 19
	s_add_u32 s4, s16, s4
	s_addc_u32 s5, s17, s5
	s_add_u32 s8, s4, 0x40000
	v_writelane_b32 v253, s4, 62
	s_addc_u32 s9, s5, 0
	v_writelane_b32 v254, s8, 0
	s_bfe_i64 s[0:1], s[0:1], 0x100000
	s_lshl_b64 s[0:1], s[0:1], 19
	v_writelane_b32 v254, s9, 1
	v_writelane_b32 v254, s0, 2
	s_ashr_i32 s19, s18, 31
	v_writelane_b32 v253, s5, 63
	v_writelane_b32 v254, s1, 3
	s_mov_b32 s0, s18
	v_writelane_b32 v254, s0, 4
	s_movk_i32 s84, 0xc000
	s_movk_i32 s70, 0x140
	v_writelane_b32 v254, s1, 5
	s_lshl_b64 s[0:1], s[18:19], 19
	s_add_u32 s0, s16, s0
	v_writelane_b32 v254, s16, 6
	s_addc_u32 s1, s17, s1
	s_add_u32 s4, s0, 0x40000
	v_writelane_b32 v254, s17, 7
	v_writelane_b32 v254, s0, 8
	s_addc_u32 s5, s1, 0
	s_ashr_i32 s7, s6, 31
	v_writelane_b32 v254, s1, 9
	v_writelane_b32 v254, s4, 10
	s_bfe_i64 s[0:1], s[2:3], 0x100000
	s_lshl_b64 s[2:3], s[6:7], 19
	v_writelane_b32 v254, s5, 11
	s_lshl_b64 s[4:5], s[0:1], 19
	v_writelane_b32 v254, s4, 12
	s_add_u32 s2, s14, s2
	s_movk_i32 s60, 0x280
	v_writelane_b32 v254, s5, 13
	v_writelane_b32 v254, s14, 14
	s_addc_u32 s3, s15, s3
	s_add_u32 s4, s2, 0x40000
	v_writelane_b32 v254, s15, 15
	v_writelane_b32 v254, s2, 16
	s_addc_u32 s5, s3, 0
	s_lshl_b64 s[0:1], s[0:1], 21
	v_writelane_b32 v254, s3, 17
	v_writelane_b32 v254, s4, 18
	s_movk_i32 s85, 0xa000
	s_movk_i32 s86, 0xb000
	v_writelane_b32 v254, s5, 19
	v_writelane_b32 v254, s0, 20
	s_movk_i32 s87, 0xe000
	s_mov_b32 s54, 0xfffed000
	v_writelane_b32 v254, s1, 21
	s_mov_b32 s0, s6
	v_writelane_b32 v254, s0, 22
	s_mov_b32 s55, 0xffff3000
	s_mov_b32 s61, 0xffff5000
	v_writelane_b32 v254, s1, 23
	s_lshl_b64 s[0:1], s[6:7], 21
	s_add_u32 s0, s10, s0
	s_addc_u32 s1, s11, s1
	s_add_u32 s2, s0, 0x100000
	v_writelane_b32 v254, s0, 24
	s_addc_u32 s3, s1, 0
	s_movk_i32 s33, 0x1200
	v_writelane_b32 v254, s1, 25
	v_writelane_b32 v254, s2, 26
	s_add_i32 s0, s12, 0xfffffe00
	v_readlane_b32 s12, v252, 16
	v_writelane_b32 v254, s3, 27
	v_writelane_b32 v254, s0, 28
	v_readlane_b32 s0, v252, 32
	v_readlane_b32 s2, v252, 34
	v_readlane_b32 s3, v252, 35
	s_add_u32 s0, s2, 0x1c000
	v_readlane_b32 s13, v252, 17
	v_readlane_b32 s14, v252, 18
	v_readlane_b32 s15, v252, 19
	v_readlane_b32 s16, v252, 20
	v_readlane_b32 s17, v252, 21
	v_readlane_b32 s18, v252, 22
	v_readlane_b32 s19, v252, 23
	v_readlane_b32 s20, v252, 24
	v_readlane_b32 s21, v252, 25
	v_writelane_b32 v254, s0, 29
	s_addc_u32 s0, s3, 0
	v_readlane_b32 s22, v252, 26
	v_readlane_b32 s23, v252, 27
	v_readlane_b32 s24, v252, 28
	v_readlane_b32 s25, v252, 29
	v_readlane_b32 s26, v252, 30
	v_readlane_b32 s27, v252, 31
	s_mov_b64 s[12:13], s[20:21]
	v_writelane_b32 v254, s0, 30
	s_lshl_b32 s0, s76, 4
	s_mov_b64 s[18:19], s[26:27]
	v_writelane_b32 v254, s0, 31
	s_add_u32 s0, s18, 0x7000
	v_writelane_b32 v254, s0, 32
	s_addc_u32 s0, s19, 0
	s_mov_b64 s[14:15], s[22:23]
	s_mov_b64 s[16:17], s[24:25]
	v_writelane_b32 v254, s0, 33
	s_add_u32 s0, s12, 8
	v_writelane_b32 v254, s0, 34
	s_addc_u32 s0, s13, 0
	v_readlane_b32 s12, v252, 0
	v_readlane_b32 s13, v252, 1
	v_readlane_b32 s14, v252, 2
	v_readlane_b32 s15, v252, 3
	v_readlane_b32 s16, v252, 4
	v_readlane_b32 s17, v252, 5
	v_readlane_b32 s18, v252, 6
	v_readlane_b32 s19, v252, 7
	s_mov_b64 s[12:13], s[16:17]
	s_mov_b64 s[14:15], s[18:19]
	v_writelane_b32 v254, s0, 35
	s_add_u32 s0, s14, 0x13978
	v_readlane_b32 s4, v252, 36
	v_writelane_b32 v254, s0, 36
	s_addc_u32 s0, s15, 0
	v_readlane_b32 s5, v252, 37
	v_writelane_b32 v254, s0, 37
	s_add_u32 s0, s4, 0x7000
	v_writelane_b32 v254, s0, 38
	s_addc_u32 s0, s5, 0
	v_writelane_b32 v254, s0, 39
	s_add_u32 s0, s10, 0x1200
	v_writelane_b32 v254, s0, 40
	s_addc_u32 s0, s11, 0
	v_readlane_b32 s1, v252, 33
	v_writelane_b32 v254, s0, 41
	s_add_u32 s0, s10, 0x1f200080
	s_addc_u32 s1, s11, 0
	v_writelane_b32 v254, s0, 42
	s_mov_b32 s95, 0xefa18f08
	s_mov_b32 s94, 0x45000000
	v_writelane_b32 v254, s1, 43
	s_add_u32 s0, s10, 0x7c0
	s_addc_u32 s1, s11, 0
	v_writelane_b32 v254, s0, 44
	s_mov_b64 s[88:89], 0x80
	s_nop 0
	v_writelane_b32 v254, s1, 45
	s_add_u32 s0, s10, 0x16800080
	s_addc_u32 s1, s11, 0
	v_writelane_b32 v254, s0, 46
	s_add_i32 s59, 0, 0x10000
	s_add_i32 s64, 0, 0x18000
	v_writelane_b32 v254, s1, 47
	s_mov_b32 s0, 1
	v_writelane_b32 v254, s0, 48
	s_add_i32 s0, 0, 0x20000
	v_writelane_b32 v254, s0, 49
	s_add_i32 s0, 0, 0x16800
	v_writelane_b32 v254, s0, 50
	s_add_i32 s0, 0, 0x13600
	v_writelane_b32 v254, s0, 51
	s_add_i32 s0, 0, 0xb000
	v_writelane_b32 v254, s0, 52
	s_mov_b32 s0, 0
	v_writelane_b32 v254, s0, 53
	v_writelane_b32 v254, s0, 54
	s_mov_b64 s[0:1], 2
	v_writelane_b32 v254, s0, 55
	s_barrier
	s_nop 0
	v_writelane_b32 v254, s1, 56
	s_mov_b64 s[0:1], 3
	v_writelane_b32 v254, s0, 57
	v_readlane_b32 s6, v252, 38
	v_readlane_b32 s7, v252, 39
	v_writelane_b32 v254, s1, 58
	s_mov_b64 s[0:1], 4
	v_writelane_b32 v254, s0, 59
	v_readlane_b32 s20, v252, 8
	v_readlane_b32 s21, v252, 9
	v_writelane_b32 v254, s1, 60
	s_mov_b64 s[0:1], 5
	v_writelane_b32 v254, s0, 61
	v_readlane_b32 s22, v252, 10
	v_readlane_b32 s23, v252, 11
	v_writelane_b32 v254, s1, 62
	s_mov_b32 s0, s93
	v_writelane_b32 v254, s0, 63
	v_readlane_b32 s24, v252, 12
	v_readlane_b32 s25, v252, 13
	v_writelane_b32 v255, s1, 0
	v_writelane_b32 v255, s52, 1
	s_mov_b32 s0, s76
	v_writelane_b32 v253, s0, 4
	v_writelane_b32 v255, s53, 2
	v_writelane_b32 v255, s65, 3
	v_writelane_b32 v255, s59, 4
	v_writelane_b32 v253, s1, 5
	v_writelane_b32 v255, s64, 5
	v_readlane_b32 s26, v252, 14
	v_readlane_b32 s27, v252, 15
	s_branch .LBB0_253
; DEVI void gbar(unsigned* ctr, unsigned& gen, int wv) {
;     ...
;       while (__hip_atomic_load(ctr, __ATOMIC_RELAXED, __HIP_MEMORY_SCOPE_AGENT) < target) { }
;     }
;     __builtin_amdgcn_fence(__ATOMIC_ACQUIRE, "agent");
;     asm volatile("s_waitcnt vmcnt(0)" ::: "memory");
;   }
;   __syncthreads();
; __global__ void __launch_bounds__(512) mega(Params p) {
;     ...
; #pragma unroll 1
;   for (int l = 0; l < 4; ++l) {
.LBB0_251:
	s_or_b64 exec, exec, s[4:5]
	s_waitcnt vmcnt(0)
.LBB0_252:
	s_or_b64 exec, exec, s[0:1]
	v_readlane_b32 s0, v254, 54
	s_add_i32 s0, s0, 6
	s_nop 0
	v_writelane_b32 v254, s0, 54
	s_barrier
	v_readlane_b32 s0, v254, 63
	s_add_i32 s2, s0, 1
	v_readlane_b32 s0, v254, 53
	s_add_i32 s0, s0, 2
	v_readlane_b32 s1, v255, 0
	v_writelane_b32 v254, s0, 53
	s_nop 0
	v_readlane_b32 s0, v254, 42
	v_readlane_b32 s1, v254, 43
	s_add_u32 s0, s0, 0x40000
	s_addc_u32 s1, s1, 0
	v_writelane_b32 v254, s0, 42
	s_nop 1
	v_writelane_b32 v254, s1, 43
	s_nop 0
	v_readlane_b32 s0, v254, 55
	v_readlane_b32 s1, v254, 56
	s_add_u32 s0, s0, 6
	s_addc_u32 s1, s1, 0
	v_writelane_b32 v254, s0, 55
	s_nop 1
	v_writelane_b32 v254, s1, 56
	s_nop 0
	v_readlane_b32 s0, v254, 57
	v_readlane_b32 s1, v254, 58
	s_add_u32 s0, s0, 6
	s_addc_u32 s1, s1, 0
	v_writelane_b32 v254, s0, 57
	s_nop 1
	v_writelane_b32 v254, s1, 58
	s_nop 0
	v_readlane_b32 s0, v254, 59
	v_readlane_b32 s1, v254, 60
	s_add_u32 s0, s0, 6
	s_addc_u32 s1, s1, 0
	v_writelane_b32 v254, s0, 59
	s_nop 1
	v_writelane_b32 v254, s1, 60
	s_nop 0
	v_readlane_b32 s0, v254, 61
	v_readlane_b32 s1, v254, 62
	s_add_u32 s0, s0, 6
	s_addc_u32 s1, s1, 0
	v_writelane_b32 v254, s0, 61
	s_cmp_eq_u32 s2, 4
	s_nop 0
	v_writelane_b32 v254, s1, 62
	s_mov_b32 s0, s2
	v_writelane_b32 v254, s0, 63
	s_nop 1
	v_writelane_b32 v255, s1, 0
	s_cbranch_scc0 .LBB0_253
	s_getpc_b64 s[98:99]

; DEVI int opaque_tid(int wv) { int t; asm volatile("v_mbcnt_lo_u32_b32 %0, -1, 0\n\tv_mbcnt_hi_u32_b32 %0, -1, %0" : "=v"(t)); return wv * 64 + t; }
; DEVI void gbar(unsigned* ctr, unsigned& gen, int wv) {
;   asm volatile("s_waitcnt vmcnt(0) lgkmcnt(0)" ::: "memory");
;   __syncthreads();
;   ++gen;
;   const int tb = opaque_tid(wv);
;   if (tb < 64) {
;     __builtin_amdgcn_fence(__ATOMIC_RELEASE, "agent");
;     asm volatile("s_waitcnt vmcnt(0)" ::: "memory");
;     if (tb == 0) {
;       __hip_atomic_fetch_add(ctr, 1u, __ATOMIC_RELAXED, __HIP_MEMORY_SCOPE_AGENT);
;       const unsigned target = gen * 256u;
;       while (__hip_atomic_load(ctr, __ATOMIC_RELAXED, __HIP_MEMORY_SCOPE_AGENT) < target) { }
.LBB0_615:
	s_barrier
	s_waitcnt vmcnt(0) lgkmcnt(0)
	s_barrier
	v_mbcnt_lo_u32_b32 v0, -1, 0
	v_mbcnt_hi_u32_b32 v0, -1, v0
	v_readlane_b32 s0, v252, 46
	s_nop 1
	v_add_u32_e32 v0, s0, v0
	v_cmp_gt_i32_e32 vcc, 64, v0
	s_and_saveexec_b64 s[0:1], vcc
	s_cbranch_execz .LBB0_622
	s_waitcnt vmcnt(0)
	buffer_inv sc1
	v_cmp_eq_u32_e32 vcc, 0, v0
	s_and_saveexec_b64 s[4:5], vcc
	s_cbranch_execz .LBB0_621
	s_getreg_b32 s8, hwreg(HW_REG_XCC_ID, 0, 4)
	s_lshl_b32 s8, s8, 2
	s_add_u32 s8, s52, s8
	s_addc_u32 s9, s53, 0
	v_mov_b32_e32 v0, 1
	global_atomic_add v0, v33, v0, s[8:9] offset:128 sc0
	v_readlane_b32 s2, v254, 48
	s_lshl_b32 s2, s2, 5
	s_addk_i32 s2, 32
	s_waitcnt vmcnt(0)
	v_readfirstlane_b32 s6, v0
	s_add_i32 s6, s6, 1
	s_cmp_lg_u32 s6, s2
	s_cbranch_scc1 .Lgb1_poll
	buffer_wbl2 sc1
	s_waitcnt vmcnt(0)
	v_mov_b32_e32 v0, 1
	global_atomic_add v33, v0, s[52:53]

; DEVI int opaque_tid(int wv) { int t; asm volatile("v_mbcnt_lo_u32_b32 %0, -1, 0\n\tv_mbcnt_hi_u32_b32 %0, -1, %0" : "=v"(t)); return wv * 64 + t; }
; DEVI void gbar(unsigned* ctr, unsigned& gen, int wv) {
;     ...
;       while (__hip_atomic_load(ctr, __ATOMIC_RELAXED, __HIP_MEMORY_SCOPE_AGENT) < target) { }
;     }
;     __builtin_amdgcn_fence(__ATOMIC_ACQUIRE, "agent");
;     asm volatile("s_waitcnt vmcnt(0)" ::: "memory");
;   }
;   __syncthreads();
; __global__ void __launch_bounds__(512) mega(Params p) {
;     ...
;   auto shadow_step = [&]() {
;     int bido = bid; asm volatile("" : "+s"(bido));
;     if (sph <= 20 && sph % 5 == 0 && sph > 0 && bido < 16) {
;       const int tid = opaque_tid(wv);
;       for (int k = tid; k < DM; k += 512) SNAP[(size_t)((sph / 5 - 1) * 16 + bido) * 1024 + k] = SX[bido * 1024 + k];
;     }
.LBB0_620:
	global_load_dword v0, v33, s[52:53] sc1
	s_waitcnt vmcnt(0)
	v_cmp_gt_u32_e32 vcc, s2, v0
	s_cbranch_vccnz .LBB0_620
.LBB0_621:
	s_or_b64 exec, exec, s[4:5]
	s_waitcnt vmcnt(0)
.LBB0_622:
	s_or_b64 exec, exec, s[0:1]
	v_readlane_b32 s0, v254, 54
	s_or_b32 s0, s0, 1
	s_mul_hi_u32 s1, s0, 0xcccccccd
	s_lshr_b32 s92, s1, 2
	s_mul_i32 s1, s92, 5
	s_sub_i32 s16, s0, s1
	s_mov_b32 s17, s76
	s_cmp_eq_u32 s16, 0
	s_barrier
	s_cselect_b64 s[0:1], -1, 0
	s_cmp_lt_i32 s17, 16
	s_cselect_b64 s[2:3], -1, 0
	s_and_b64 s[0:1], s[0:1], s[2:3]
	s_andn2_b64 vcc, exec, s[0:1]
	s_cbranch_vccnz .LBB0_627
	v_readlane_b32 s0, v252, 46
	v_mbcnt_lo_u32_b32 v0, -1, 0
	v_mbcnt_hi_u32_b32 v0, -1, v0
	s_nop 1
	v_add_u32_e32 v2, s0, v0
	s_movk_i32 s0, 0x400
	v_cmp_gt_i32_e32 vcc, s0, v2
	s_and_saveexec_b64 s[0:1], vcc
	s_movk_i32 s6, 0x1ff
	s_mov_b64 s[8:9], 0x800
	s_cbranch_execz .LBB0_626
	v_readlane_b32 s2, v254, 48
	s_mul_hi_u32 s2, s2, 0xcccccccd
	s_lshl_b32 s2, s2, 2
	s_and_b32 s2, s2, -16
	s_add_i32 s2, s17, s2
	v_readlane_b32 s3, v254, 28
	s_add_i32 s2, s2, -16
	v_readlane_b32 s4, v253, 20
	v_add_u32_e32 v4, s3, v0
	s_ashr_i32 s3, s2, 31
	s_lshl_b64 s[2:3], s[2:3], 12
	s_add_u32 s2, s4, s2
	v_readlane_b32 s4, v253, 21
	v_ashrrev_i32_e32 v3, 31, v2
	s_addc_u32 s3, s4, s3
	v_lshl_add_u64 v[0:1], v[2:3], 2, s[2:3]
	v_lshl_add_u32 v2, s17, 10, v2
	v_readlane_b32 s2, v253, 12
	v_ashrrev_i32_e32 v3, 31, v2
	v_readlane_b32 s3, v253, 13
	s_mov_b64 s[4:5], 0
	s_nop 0
	v_lshl_add_u64 v[2:3], v[2:3], 2, s[2:3]

; DEVI int opaque_tid(int wv) { int t; asm volatile("v_mbcnt_lo_u32_b32 %0, -1, 0\n\tv_mbcnt_hi_u32_b32 %0, -1, %0" : "=v"(t)); return wv * 64 + t; }
; DEVI void gbar(unsigned* ctr, unsigned& gen, int wv) {
;   asm volatile("s_waitcnt vmcnt(0) lgkmcnt(0)" ::: "memory");
;   __syncthreads();
;   ++gen;
;   const int tb = opaque_tid(wv);
;   if (tb < 64) {
;     __builtin_amdgcn_fence(__ATOMIC_RELEASE, "agent");
;     asm volatile("s_waitcnt vmcnt(0)" ::: "memory");
;     if (tb == 0) {
;       __hip_atomic_fetch_add(ctr, 1u, __ATOMIC_RELAXED, __HIP_MEMORY_SCOPE_AGENT);
;       const unsigned target = gen * 256u;
;       while (__hip_atomic_load(ctr, __ATOMIC_RELAXED, __HIP_MEMORY_SCOPE_AGENT) < target) { }
.LBB0_988:
	s_waitcnt vmcnt(0) lgkmcnt(0)
	s_barrier
	v_mbcnt_lo_u32_b32 v0, -1, 0
	v_mbcnt_hi_u32_b32 v0, -1, v0
	v_readlane_b32 s0, v252, 46
	s_nop 1
	v_add_u32_e32 v0, s0, v0
	v_cmp_gt_i32_e32 vcc, 64, v0
	s_and_saveexec_b64 s[0:1], vcc
	s_cbranch_execz .LBB0_995
	s_waitcnt vmcnt(0)
	buffer_inv sc1
	v_cmp_eq_u32_e32 vcc, 0, v0
	s_and_saveexec_b64 s[4:5], vcc
	s_cbranch_execz .LBB0_994
	s_getreg_b32 s10, hwreg(HW_REG_XCC_ID, 0, 4)
	s_lshl_b32 s10, s10, 2
	s_add_u32 s10, s52, s10
	s_addc_u32 s11, s53, 0
	v_mov_b32_e32 v0, 1
	global_atomic_add v0, v33, v0, s[10:11] offset:128 sc0
	v_readlane_b32 s2, v254, 48
	s_lshl_b32 s2, s2, 5
	s_addk_i32 s2, 64
	s_waitcnt vmcnt(0)
	v_readfirstlane_b32 s6, v0
	s_add_i32 s6, s6, 1
	s_cmp_lg_u32 s6, s2
	s_cbranch_scc1 .Lgb2_poll
	buffer_wbl2 sc1
	s_waitcnt vmcnt(0)
	v_mov_b32_e32 v0, 1
	global_atomic_add v33, v0, s[52:53]

; DEVI void gbar(unsigned* ctr, unsigned& gen, int wv) {
;     ...
;       while (__hip_atomic_load(ctr, __ATOMIC_RELAXED, __HIP_MEMORY_SCOPE_AGENT) < target) { }
;     }
;     __builtin_amdgcn_fence(__ATOMIC_ACQUIRE, "agent");
;     asm volatile("s_waitcnt vmcnt(0)" ::: "memory");
;   }
;   __syncthreads();
.LBB0_993:
	global_load_dword v0, v33, s[52:53] sc1
	s_waitcnt vmcnt(0)
	v_cmp_gt_u32_e32 vcc, s2, v0
	s_cbranch_vccnz .LBB0_993
.LBB0_994:
	s_or_b64 exec, exec, s[4:5]
	s_waitcnt vmcnt(0)

; DEVI int opaque_tid(int wv) { int t; asm volatile("v_mbcnt_lo_u32_b32 %0, -1, 0\n\tv_mbcnt_hi_u32_b32 %0, -1, %0" : "=v"(t)); return wv * 64 + t; }
; DEVI void gbar(unsigned* ctr, unsigned& gen, int wv) {
;   asm volatile("s_waitcnt vmcnt(0) lgkmcnt(0)" ::: "memory");
;   __syncthreads();
;   ++gen;
;   const int tb = opaque_tid(wv);
;   if (tb < 64) {
;     __builtin_amdgcn_fence(__ATOMIC_RELEASE, "agent");
;     asm volatile("s_waitcnt vmcnt(0)" ::: "memory");
;     if (tb == 0) {
;       __hip_atomic_fetch_add(ctr, 1u, __ATOMIC_RELAXED, __HIP_MEMORY_SCOPE_AGENT);
;       const unsigned target = gen * 256u;
;       while (__hip_atomic_load(ctr, __ATOMIC_RELAXED, __HIP_MEMORY_SCOPE_AGENT) < target) { }
.LBB0_1496:
	s_waitcnt vmcnt(0) lgkmcnt(0)
	s_barrier
	v_mbcnt_lo_u32_b32 v0, -1, 0
	v_mbcnt_hi_u32_b32 v0, -1, v0
	v_readlane_b32 s0, v252, 46
	s_nop 1
	v_add_u32_e32 v0, s0, v0
	v_cmp_gt_i32_e32 vcc, 64, v0
	s_mov_b64 s[0:1], exec
	v_readlane_b32 s76, v253, 4
	v_readlane_b32 s77, v253, 5
	v_readlane_b32 s52, v255, 1
	v_readlane_b32 s54, v253, 22
	v_readlane_b32 s56, v253, 24
	s_and_b64 s[2:3], s[0:1], vcc
	v_readlane_b32 s53, v255, 2
	v_readlane_b32 s55, v253, 23
	v_readlane_b32 s57, v253, 25
	v_readlane_b32 s65, v255, 3
	s_movk_i32 s74, 0xffc0
	v_readlane_b32 s59, v255, 4
	v_readlane_b32 s64, v255, 5
	s_movk_i32 s75, 0x2ff
	s_mov_b32 s77, 0x800000
	s_mov_b32 s78, 0xfffe4000
	s_mov_b32 s79, 0xfffe8000
	s_mov_b32 s80, 0xfffec000
	s_mov_b32 s81, 0xffff0000
	s_mov_b32 s82, 0xffff4000
	s_movk_i32 s83, 0x8000
	s_movk_i32 s84, 0xc000
	s_movk_i32 s70, 0x140
	s_movk_i32 s85, 0xa000
	s_movk_i32 s86, 0xb000
	s_movk_i32 s87, 0xe000
	s_mov_b64 exec, s[2:3]
	s_cbranch_execz .LBB0_1503
	s_waitcnt vmcnt(0)
	buffer_inv sc1
	v_cmp_eq_u32_e32 vcc, 0, v0
	s_and_saveexec_b64 s[4:5], vcc
	s_cbranch_execz .LBB0_1502
	s_getreg_b32 s8, hwreg(HW_REG_XCC_ID, 0, 4)
	s_lshl_b32 s8, s8, 2
	s_add_u32 s8, s52, s8
	s_addc_u32 s9, s53, 0
	v_mov_b32_e32 v0, 1
	global_atomic_add v0, v33, v0, s[8:9] offset:128 sc0
	v_readlane_b32 s2, v254, 48
	s_lshl_b32 s2, s2, 5
	s_addk_i32 s2, 96
	s_waitcnt vmcnt(0)
	v_readfirstlane_b32 s6, v0
	s_add_i32 s6, s6, 1
	s_cmp_lg_u32 s6, s2
	s_cbranch_scc1 .Lgb3_poll
	buffer_wbl2 sc1
	s_waitcnt vmcnt(0)
	v_mov_b32_e32 v0, 1
	global_atomic_add v33, v0, s[52:53]

; DEVI int opaque_tid(int wv) { int t; asm volatile("v_mbcnt_lo_u32_b32 %0, -1, 0\n\tv_mbcnt_hi_u32_b32 %0, -1, %0" : "=v"(t)); return wv * 64 + t; }
; DEVI void gbar(unsigned* ctr, unsigned& gen, int wv) {
;     ...
;       while (__hip_atomic_load(ctr, __ATOMIC_RELAXED, __HIP_MEMORY_SCOPE_AGENT) < target) { }
;     }
;     __builtin_amdgcn_fence(__ATOMIC_ACQUIRE, "agent");
;     asm volatile("s_waitcnt vmcnt(0)" ::: "memory");
;   }
;   __syncthreads();
; __global__ void __launch_bounds__(512) mega(Params p) {
;     ...
;   auto shadow_step = [&]() {
;     int bido = bid; asm volatile("" : "+s"(bido));
;     if (sph <= 20 && sph % 5 == 0 && sph > 0 && bido < 16) {
;       const int tid = opaque_tid(wv);
;       for (int k = tid; k < DM; k += 512) SNAP[(size_t)((sph / 5 - 1) * 16 + bido) * 1024 + k] = SX[bido * 1024 + k];
;     }
.LBB0_1501:
	global_load_dword v0, v33, s[52:53] sc1
	s_waitcnt vmcnt(0)
	v_cmp_gt_u32_e32 vcc, s2, v0
	s_cbranch_vccnz .LBB0_1501
.LBB0_1502:
	s_or_b64 exec, exec, s[4:5]
	s_waitcnt vmcnt(0)
.LBB0_1503:
	s_or_b64 exec, exec, s[0:1]
	v_readlane_b32 s0, v254, 54
	s_add_i32 s20, s0, 3
	s_mul_hi_u32 s0, s20, 0xcccccccd
	s_lshr_b32 s0, s0, 2
	s_mul_i32 s0, s0, 5
	s_sub_i32 s22, s20, s0
	s_cmp_eq_u32 s22, 0
	v_readlane_b32 s2, v255, 7
	s_cselect_b64 s[0:1], -1, 0
	v_readlane_b32 s3, v255, 8
	s_mov_b32 s21, s76
	s_and_b64 s[0:1], s[2:3], s[0:1]
	s_barrier
	s_cmp_lt_i32 s21, 16
	s_cselect_b64 s[2:3], -1, 0
	s_and_b64 s[0:1], s[0:1], s[2:3]
	s_andn2_b64 vcc, exec, s[0:1]
	s_cbranch_vccnz .LBB0_1508
	v_readlane_b32 s0, v252, 46
	v_mbcnt_lo_u32_b32 v0, -1, 0
	v_mbcnt_hi_u32_b32 v0, -1, v0
	s_nop 1
	v_add_u32_e32 v2, s0, v0
	s_movk_i32 s0, 0x400
	v_cmp_gt_i32_e32 vcc, s0, v2
	s_and_saveexec_b64 s[0:1], vcc
	s_mov_b64 s[6:7], 0x800
	s_cbranch_execz .LBB0_1507
	v_readlane_b32 s2, v254, 57
	s_mul_hi_u32 s2, s2, 0xcccccccd
	s_lshl_b32 s2, s2, 2
	s_and_b32 s2, s2, -16
	v_readlane_b32 s3, v254, 58
	s_add_i32 s2, s21, s2
	v_readlane_b32 s3, v254, 28
	s_add_i32 s2, s2, -16
	v_readlane_b32 s4, v253, 20
	v_add_u32_e32 v4, s3, v0
	s_ashr_i32 s3, s2, 31
	s_lshl_b64 s[2:3], s[2:3], 12
	s_add_u32 s2, s4, s2
	v_readlane_b32 s4, v253, 21
	v_ashrrev_i32_e32 v3, 31, v2
	s_addc_u32 s3, s4, s3
	v_lshl_add_u64 v[0:1], v[2:3], 2, s[2:3]
	v_lshl_add_u32 v2, s21, 10, v2
	v_readlane_b32 s2, v253, 12
	v_ashrrev_i32_e32 v3, 31, v2
	v_readlane_b32 s3, v253, 13
	s_mov_b64 s[4:5], 0
	s_nop 0
	v_lshl_add_u64 v[2:3], v[2:3], 2, s[2:3]

; DEVI int opaque_tid(int wv) { int t; asm volatile("v_mbcnt_lo_u32_b32 %0, -1, 0\n\tv_mbcnt_hi_u32_b32 %0, -1, %0" : "=v"(t)); return wv * 64 + t; }
; DEVI void gbar(unsigned* ctr, unsigned& gen, int wv) {
;   asm volatile("s_waitcnt vmcnt(0) lgkmcnt(0)" ::: "memory");
;   __syncthreads();
;   ++gen;
;   const int tb = opaque_tid(wv);
;   if (tb < 64) {
;     __builtin_amdgcn_fence(__ATOMIC_RELEASE, "agent");
;     asm volatile("s_waitcnt vmcnt(0)" ::: "memory");
;     if (tb == 0) {
;       __hip_atomic_fetch_add(ctr, 1u, __ATOMIC_RELAXED, __HIP_MEMORY_SCOPE_AGENT);
;       const unsigned target = gen * 256u;
;       while (__hip_atomic_load(ctr, __ATOMIC_RELAXED, __HIP_MEMORY_SCOPE_AGENT) < target) { }
.LBB0_1745:
	s_waitcnt lgkmcnt(0)
	s_barrier
	s_waitcnt vmcnt(0) lgkmcnt(0)
	s_barrier
	v_mbcnt_lo_u32_b32 v0, -1, 0
	v_mbcnt_hi_u32_b32 v0, -1, v0
	v_readlane_b32 s2, v252, 46
	s_nop 1
	v_add_u32_e32 v0, s2, v0
	v_cmp_gt_i32_e32 vcc, 64, v0
	s_and_saveexec_b64 s[4:5], vcc
	s_cbranch_execz .LBB0_1752
	s_waitcnt vmcnt(0)
	buffer_inv sc1
	v_cmp_eq_u32_e32 vcc, 0, v0
	s_and_saveexec_b64 s[6:7], vcc
	s_cbranch_execz .LBB0_1751
	s_getreg_b32 s12, hwreg(HW_REG_XCC_ID, 0, 4)
	s_lshl_b32 s12, s12, 2
	s_add_u32 s12, s52, s12
	s_addc_u32 s13, s53, 0
	v_mov_b32_e32 v0, 1
	global_atomic_add v0, v33, v0, s[12:13] offset:128 sc0
	v_readlane_b32 s2, v254, 48
	s_lshl_b32 s2, s2, 5
	s_addk_i32 s2, 128
	s_waitcnt vmcnt(0)
	v_readfirstlane_b32 s10, v0
	s_add_i32 s10, s10, 1
	s_cmp_lg_u32 s10, s2
	s_cbranch_scc1 .Lgb4_poll
	buffer_wbl2 sc1
	s_waitcnt vmcnt(0)
	v_mov_b32_e32 v0, 1
	global_atomic_add v33, v0, s[52:53]

; DEVI int opaque_tid(int wv) { int t; asm volatile("v_mbcnt_lo_u32_b32 %0, -1, 0\n\tv_mbcnt_hi_u32_b32 %0, -1, %0" : "=v"(t)); return wv * 64 + t; }
; DEVI void gbar(unsigned* ctr, unsigned& gen, int wv) {
;     ...
;       while (__hip_atomic_load(ctr, __ATOMIC_RELAXED, __HIP_MEMORY_SCOPE_AGENT) < target) { }
;     }
;     __builtin_amdgcn_fence(__ATOMIC_ACQUIRE, "agent");
;     asm volatile("s_waitcnt vmcnt(0)" ::: "memory");
;   }
;   __syncthreads();
; __global__ void __launch_bounds__(512) mega(Params p) {
;     ...
;   auto shadow_step = [&]() {
;     int bido = bid; asm volatile("" : "+s"(bido));
;     if (sph <= 20 && sph % 5 == 0 && sph > 0 && bido < 16) {
;       const int tid = opaque_tid(wv);
;       for (int k = tid; k < DM; k += 512) SNAP[(size_t)((sph / 5 - 1) * 16 + bido) * 1024 + k] = SX[bido * 1024 + k];
;     }
.LBB0_1750:
	global_load_dword v0, v33, s[52:53] sc1
	s_waitcnt vmcnt(0)
	v_cmp_gt_u32_e32 vcc, s2, v0
	s_cbranch_vccnz .LBB0_1750
.LBB0_1751:
	s_or_b64 exec, exec, s[6:7]
	s_waitcnt vmcnt(0)
.LBB0_1752:
	s_or_b64 exec, exec, s[4:5]
	v_readlane_b32 s2, v254, 54
	s_add_i32 s22, s2, 4
	s_mul_hi_u32 s2, s22, 0xcccccccd
	s_lshr_b32 s2, s2, 2
	s_mul_i32 s2, s2, 5
	s_sub_i32 s24, s22, s2
	s_cmp_eq_u32 s24, 0
	s_cselect_b64 s[2:3], -1, 0
	s_mov_b32 s23, s76
	s_and_b64 s[2:3], s[8:9], s[2:3]
	s_barrier
	s_cmp_lt_i32 s23, 16
	s_cselect_b64 s[4:5], -1, 0
	s_and_b64 s[2:3], s[2:3], s[4:5]
	s_andn2_b64 vcc, exec, s[2:3]
	s_cbranch_vccnz .LBB0_1757
	v_readlane_b32 s2, v252, 46
	v_mbcnt_lo_u32_b32 v0, -1, 0
	v_mbcnt_hi_u32_b32 v0, -1, v0
	s_nop 1
	v_add_u32_e32 v2, s2, v0
	s_movk_i32 s2, 0x400
	v_cmp_gt_i32_e32 vcc, s2, v2
	s_and_saveexec_b64 s[4:5], vcc
	s_mov_b64 s[8:9], 0x800
	s_cbranch_execz .LBB0_1756
	v_readlane_b32 s2, v254, 59
	s_mul_hi_u32 s2, s2, 0xcccccccd
	s_lshl_b32 s2, s2, 2
	s_and_b32 s2, s2, -16
	v_readlane_b32 s3, v254, 60
	s_add_i32 s2, s23, s2
	v_readlane_b32 s3, v254, 28
	s_add_i32 s2, s2, -16
	v_readlane_b32 s6, v253, 20
	v_add_u32_e32 v4, s3, v0
	s_ashr_i32 s3, s2, 31
	s_lshl_b64 s[2:3], s[2:3], 12
	s_add_u32 s2, s6, s2
	v_readlane_b32 s6, v253, 21
	v_ashrrev_i32_e32 v3, 31, v2
	s_addc_u32 s3, s6, s3
	v_lshl_add_u64 v[0:1], v[2:3], 2, s[2:3]
	v_lshl_add_u32 v2, s23, 10, v2
	v_readlane_b32 s2, v253, 12
	v_ashrrev_i32_e32 v3, 31, v2
	v_readlane_b32 s3, v253, 13
	s_mov_b64 s[6:7], 0
	s_nop 0
	v_lshl_add_u64 v[2:3], v[2:3], 2, s[2:3]

; DEVI int opaque_tid(int wv) { int t; asm volatile("v_mbcnt_lo_u32_b32 %0, -1, 0\n\tv_mbcnt_hi_u32_b32 %0, -1, %0" : "=v"(t)); return wv * 64 + t; }
; DEVI void gbar(unsigned* ctr, unsigned& gen, int wv) {
;   asm volatile("s_waitcnt vmcnt(0) lgkmcnt(0)" ::: "memory");
;   __syncthreads();
;   ++gen;
;   const int tb = opaque_tid(wv);
;   if (tb < 64) {
;     __builtin_amdgcn_fence(__ATOMIC_RELEASE, "agent");
;     asm volatile("s_waitcnt vmcnt(0)" ::: "memory");
;     if (tb == 0) {
;       __hip_atomic_fetch_add(ctr, 1u, __ATOMIC_RELAXED, __HIP_MEMORY_SCOPE_AGENT);
;       const unsigned target = gen * 256u;
;       while (__hip_atomic_load(ctr, __ATOMIC_RELAXED, __HIP_MEMORY_SCOPE_AGENT) < target) { }
.LBB0_1978:
	s_barrier
	s_waitcnt vmcnt(0) lgkmcnt(0)
	s_barrier
	v_mbcnt_lo_u32_b32 v0, -1, 0
	v_mbcnt_hi_u32_b32 v0, -1, v0
	v_readlane_b32 s2, v252, 46
	s_nop 1
	v_add_u32_e32 v0, s2, v0
	v_cmp_gt_i32_e32 vcc, 64, v0
	s_and_saveexec_b64 s[4:5], vcc
	s_cbranch_execz .LBB0_1985
	s_waitcnt vmcnt(0)
	buffer_inv sc1
	v_cmp_eq_u32_e32 vcc, 0, v0
	s_and_saveexec_b64 s[6:7], vcc
	s_cbranch_execz .LBB0_1984
	s_getreg_b32 s14, hwreg(HW_REG_XCC_ID, 0, 4)
	s_lshl_b32 s14, s14, 2
	s_add_u32 s14, s52, s14
	s_addc_u32 s15, s53, 0
	v_mov_b32_e32 v0, 1
	global_atomic_add v0, v33, v0, s[14:15] offset:128 sc0
	v_readlane_b32 s2, v254, 48
	s_lshl_b32 s2, s2, 5
	s_addk_i32 s2, 160
	s_waitcnt vmcnt(0)
	v_readfirstlane_b32 s8, v0
	s_add_i32 s8, s8, 1
	s_cmp_lg_u32 s8, s2
	s_cbranch_scc1 .Lgb5_poll
	buffer_wbl2 sc1
	s_waitcnt vmcnt(0)
	v_mov_b32_e32 v0, 1
	global_atomic_add v33, v0, s[52:53]

; DEVI int opaque_tid(int wv) { int t; asm volatile("v_mbcnt_lo_u32_b32 %0, -1, 0\n\tv_mbcnt_hi_u32_b32 %0, -1, %0" : "=v"(t)); return wv * 64 + t; }
; DEVI void gbar(unsigned* ctr, unsigned& gen, int wv) {
;     ...
;       while (__hip_atomic_load(ctr, __ATOMIC_RELAXED, __HIP_MEMORY_SCOPE_AGENT) < target) { }
;     }
;     __builtin_amdgcn_fence(__ATOMIC_ACQUIRE, "agent");
;     asm volatile("s_waitcnt vmcnt(0)" ::: "memory");
;   }
;   __syncthreads();
; __global__ void __launch_bounds__(512) mega(Params p) {
;     ...
;   auto shadow_step = [&]() {
;     int bido = bid; asm volatile("" : "+s"(bido));
;     if (sph <= 20 && sph % 5 == 0 && sph > 0 && bido < 16) {
;       const int tid = opaque_tid(wv);
;       for (int k = tid; k < DM; k += 512) SNAP[(size_t)((sph / 5 - 1) * 16 + bido) * 1024 + k] = SX[bido * 1024 + k];
;     }
.LBB0_1983:
	global_load_dword v0, v33, s[52:53] sc1
	s_waitcnt vmcnt(0)
	v_cmp_gt_u32_e32 vcc, s2, v0
	s_cbranch_vccnz .LBB0_1983
.LBB0_1984:
	s_or_b64 exec, exec, s[6:7]
	s_waitcnt vmcnt(0)
.LBB0_1985:
	s_or_b64 exec, exec, s[4:5]
	v_readlane_b32 s2, v254, 54
	s_add_i32 s22, s2, 5
	s_mul_hi_u32 s2, s22, 0xcccccccd
	s_lshr_b32 s2, s2, 2
	s_mul_i32 s2, s2, 5
	s_sub_i32 s24, s22, s2
	s_cmp_eq_u32 s24, 0
	s_cselect_b64 s[2:3], -1, 0
	s_mov_b32 s23, s76
	s_and_b64 s[2:3], s[12:13], s[2:3]
	s_barrier
	s_cmp_lt_i32 s23, 16
	s_cselect_b64 s[4:5], -1, 0
	s_and_b64 s[2:3], s[2:3], s[4:5]
	s_andn2_b64 vcc, exec, s[2:3]
	s_cbranch_vccnz .LBB0_1990
	v_readlane_b32 s2, v252, 46
	v_mbcnt_lo_u32_b32 v0, -1, 0
	v_mbcnt_hi_u32_b32 v0, -1, v0
	s_nop 1
	v_add_u32_e32 v2, s2, v0
	s_movk_i32 s2, 0x400
	v_cmp_gt_i32_e32 vcc, s2, v2
	s_and_saveexec_b64 s[4:5], vcc
	s_mov_b64 s[8:9], 0x800
	s_cbranch_execz .LBB0_1989
	v_readlane_b32 s2, v254, 61
	s_mul_hi_u32 s2, s2, 0xcccccccd
	s_lshl_b32 s2, s2, 2
	s_and_b32 s2, s2, -16
	v_readlane_b32 s3, v254, 62
	s_add_i32 s2, s23, s2
	v_readlane_b32 s3, v254, 28
	s_add_i32 s2, s2, -16
	v_readlane_b32 s6, v253, 20
	v_add_u32_e32 v4, s3, v0
	s_ashr_i32 s3, s2, 31
	s_lshl_b64 s[2:3], s[2:3], 12
	s_add_u32 s2, s6, s2
	v_readlane_b32 s6, v253, 21
	v_ashrrev_i32_e32 v3, 31, v2
	s_addc_u32 s3, s6, s3
	v_lshl_add_u64 v[0:1], v[2:3], 2, s[2:3]
	v_lshl_add_u32 v2, s23, 10, v2
	v_readlane_b32 s2, v253, 12
	v_ashrrev_i32_e32 v3, 31, v2
	v_readlane_b32 s3, v253, 13
	s_mov_b64 s[6:7], 0
	s_nop 0
	v_lshl_add_u64 v[2:3], v[2:3], 2, s[2:3]

; DEVI void gbar(unsigned* ctr, unsigned& gen, int wv) {
;     ...
;   if (tb < 64) {
;     __builtin_amdgcn_fence(__ATOMIC_RELEASE, "agent");
;     asm volatile("s_waitcnt vmcnt(0)" ::: "memory");
;     if (tb == 0) {
;       __hip_atomic_fetch_add(ctr, 1u, __ATOMIC_RELAXED, __HIP_MEMORY_SCOPE_AGENT);
.LBB0_2236:
	s_waitcnt vmcnt(0)
	buffer_inv sc1
	v_cmp_eq_u32_e32 vcc, 0, v0
	s_and_saveexec_b64 s[4:5], vcc
	s_cbranch_execnz .LBB0_2237
	s_getpc_b64 s[98:99]
